# PREP: conversion items redistributed by workgroup class (gate-tile workgroups take 3-5 items, the others 5-8) using the re-entrant conversion loop
# speedup vs baseline: 1.0105x; 1.0105x over previous
; __device__ __forceinline__ float w_qscale(float wmax) { return exp2f(floorf(log2f(128.f / fmaxf(wmax, 1e-30f)))); }
; __device__ __forceinline__ bool witem_decode(const Frame& F, int l, int it, WItem& t) {
;     ...
;     if (r < N_GU) { const int le = l * NE + r / I_GU; t.W = F.in[16] + (size_t)le * D * 2048; t.WT = (unsigned char*)(F.ws + WS_WGU) + (size_t)le * 2048 * D; t.N = 2048; t.map = 1; nblk = 16; item = r % I_GU; t.scale = w_qscale(wmax[l * 2 + 0]); }
;     else if ((r -= N_GU) < N_DN) { const int le = l * NE + r / I_DN; t.W = F.in[18] + (size_t)le * FF * D; t.WT = (unsigned char*)(F.ws + WS_WDN) + (size_t)le * D * FF; t.N = D; t.map = 3; nblk = 8; item = r % I_DN; t.scale = w_qscale(wmax[l * 2 + 1]); }
;     else return false;
;     t.k0 = 256 * (item / nblk); t.n0 = 128 * (item % nblk); return true;
; __device__ __forceinline__ void phase_prep(const Frame& F, int l) {
;     ...
;         if (F.bid >= first) {
;             conv_tokens(F, l, first); for (int u = F.bid - first; u < NB * 4 * 16; u += F.G - first) ret_kv_unit(F, u); __syncthreads();
;             gates_tiles(F, l, first);
;             fp8_convert_range(F, l, F.bid - first, F.G - first, CONV_SPLIT);
.LBB0_1345:
	s_movk_i32 s100, 0x600
	v_readlane_b32 s0, v250, 30
	v_readlane_b32 s1, v250, 31
	s_andn2_b64 vcc, exec, s[0:1]
	s_barrier
	s_cbranch_vccnz .LBB0_1354
	s_cmp_lg_u32 s81, 0x100
	s_cbranch_scc1 .Lcvt_entry
	s_movk_i32 s3, 0x280
	s_cmp_lg_u32 s96, 0
	s_cselect_b32 s1, 0x240, 0
	s_cselect_b32 s3, 0x180, s3
	s_cmp_lt_u32 s80, 0x80
	s_cbranch_scc1 .Lpb_low
	s_sub_i32 s0, s80, 0x80
	s_add_i32 s0, s0, s1
	s_add_i32 s100, s1, s3
	s_movk_i32 s74, 0x80
	s_branch .Lpb_set
.Lpb_low:
	s_sub_i32 s0, 0x7f, s80
	s_add_i32 s0, s0, s1
	s_add_i32 s0, s0, s3
	s_movk_i32 s100, 0x600
	s_movk_i32 s74, 0x70
.Lpb_set:
	s_lshr_b32 s1, s0, 6
	s_and_b32 s3, s0, 63
	s_lshr_b32 s5, s3, 4
	s_lshl_b32 s5, s5, 8
	s_and_b32 s3, s3, 15
	s_lshl_b32 s3, s3, 7
	s_mov_b32 s6, 0
	v_writelane_b32 v248, s1, 41
	v_writelane_b32 v248, s0, 42
	v_writelane_b32 v248, s5, 43
	v_writelane_b32 v248, s3, 44
	v_writelane_b32 v248, s6, 45
	s_mov_b32 s101, 3

; #define SEAM(k) do { if (IN(k) && IN((k) + 1)) xcd_barrier(bar, is_t0); } while (0)
; __device__ __forceinline__ void xcd_barrier(const XcdBarrier& b, const bool is_t0) {
;     asm volatile("s_waitcnt vmcnt(0)" ::: "memory");
;     __syncthreads();
;     if (is_t0) {
;         unsigned* bar = b.bar;
;         __builtin_amdgcn_s_waitcnt(0);
;         unsigned nloc = b.st[0], nx = b.st[1];
;         if (nloc == 0u) { xcd_barrier_complete(bar, b.x, nloc, nx); b.st[0] = nloc; b.st[1] = nx; }
; __global__ void __launch_bounds__(NTHR, 2) fwd(Args args) {
;     ...
;         if ((PMASK & 8) && IN(pb + 1)) { for (int rep = 0; rep < REPS(8); ++rep) { F = launder(F); phase_prep(F, l); if (REPS(8) > 1) __syncthreads(); } SEAM(pb + 1); }
.LBB0_1354:
	s_barrier
	s_cmp_eq_u32 s101, 3
	s_cbranch_scc1 .Lpb_ret
	s_cmp_lg_u32 s101, 0
	s_cbranch_scc1 .Ltc_ret
	s_branch .Lpb_done
.Lpb_ret:
	s_mov_b32 s101, 0
	v_readlane_b32 s74, v249, 46
.Lpb_done:
.LBB0_1355:
	v_readlane_b32 s0, v249, 55
	s_or_b32 s3, s0, 4
	v_readlane_b32 s4, v251, 8
	v_readlane_b32 s5, v251, 9
	s_cmp_gt_i32 s4, s3
	s_cselect_b64 s[0:1], -1, 0
	s_cmp_ge_i32 s3, s5
	s_cselect_b64 s[4:5], -1, 0
	s_or_b64 s[0:1], s[0:1], s[4:5]
	s_and_b64 vcc, exec, s[0:1]
	s_cbranch_vccnz .LBB0_1367
	s_waitcnt vmcnt(0)
	s_barrier
	s_mov_b64 s[0:1], exec
	v_readlane_b32 s4, v251, 6
	v_readlane_b32 s5, v251, 7
	v_readlane_b32 s28, v249, 44
	s_and_b64 s[4:5], s[0:1], s[4:5]
	v_readlane_b32 s29, v249, 45
	s_mov_b64 exec, s[4:5]
	s_cbranch_execz .LBB0_1405
	v_readlane_b32 s4, v249, 33
	s_waitcnt vmcnt(0) expcnt(0) lgkmcnt(0)
	s_nop 0
	v_mov_b32_e32 v1, s4
	ds_read_b32 v3, v1
	v_readlane_b32 s4, v249, 34
	s_waitcnt lgkmcnt(0)
	v_cmp_ne_u32_e32 vcc, 0, v3
	v_mov_b32_e32 v1, s4
	ds_read_b32 v2, v1
	s_cbranch_vccnz .LBB0_1373
	v_readlane_b32 s6, v251, 4
	v_readlane_b32 s7, v251, 5
	s_load_dwordx2 s[4:5], s[6:7], 0x4
	s_mov_b32 s11, 1
	s_waitcnt lgkmcnt(0)
	s_mul_i32 s10, s4, s81
	s_mul_i32 s10, s10, s5
	s_branch .LBB0_1360
